# P1 K-tile rotation a+b; prologue x/mem bf16 conversion unrolled 8x with block-contiguous mapping; attention epilogues (MLA, xattn) gate loads hoisted and issued together
# speedup vs baseline: 1.0122x; 1.0122x over previous
; DEV int otid() { int t = threadIdx.x; asm volatile("" : "+v"(t)); return t; }
; DEV int obid() { int t = __builtin_amdgcn_readfirstlane(*(volatile int*)(smem_g + 147456 + 8)); asm volatile("" : "+s"(t)); return t; }
; DEV int onb() { int t = gridDim.x; asm volatile("" : "+s"(t)); return t; }
; DEV void store4(bf16_t* p, f32x4 v) { *(u32x2*)p = (u32x2){pk_bf16(v[0], v[1]), pk_bf16(v[2], v[3])}; }
; DEV void phase_prologue(const Params& p, char* smem) {
;     ...
;     {
;         const size_t n4 = (size_t)T_TOK * 1024 / 4; bf16_t* xb = (bf16_t*)p.out;
;         for (size_t i = (size_t)obid() * NTHR + otid(); i < n4; i += (size_t)onb() * NTHR) { const f32x4 v = *(const f32x4*)(p.x + i * 4); store4(xb + i * 4, v); }
;     }
.LBB0_94:
	s_mov_b64 s[2:3], src_shared_base
	s_cmp_lg_u32 s0, -1
	s_cselect_b32 s2, s0, 0
	s_cselect_b32 s3, s3, 0
	v_mov_b32_e32 v2, s2
	v_mov_b32_e32 v3, s3
	flat_load_dword v1, v[2:3] sc0 sc1
	s_waitcnt vmcnt(0)
	v_mov_b32_e32 v2, v163
	s_waitcnt lgkmcnt(0)
	v_readfirstlane_b32 s2, v1
	s_ashr_i32 s3, s2, 31
	s_lshl_b64 s[2:3], s[2:3], 9
	v_ashrrev_i32_e32 v3, 31, v2
	v_lshl_add_u64 v[2:3], s[2:3], 0, v[2:3]
	s_mov_b64 s[2:3], 0x1000000
	v_cmp_gt_u64_e32 vcc, s[2:3], v[2:3]
	s_and_saveexec_b64 s[2:3], vcc
	s_cbranch_execz .LBB0_97
	s_load_dword s14, s[6:7], 0x10
	s_mov_b64 s[4:5], 0
	s_waitcnt lgkmcnt(0)
	s_lshr_b32 s14, s14, 16
	s_cmp_lg_u32 s14, 0
	s_cselect_b64 s[14:15], -1, 0
	s_cmp_lg_u64 s[14:15], 0
	s_addc_u32 s16, s50, 0
	s_mov_b64 s[14:15], 0xffffff
	s_lshl_b32 s40, s16, 12
	s_mov_b32 s41, 0
	s_mov_b64 s[38:39], 0x2000
	s_mov_b64 s[46:47], 0x1000
	s_mov_b32 s44, 0
	v_lshlrev_b32_e32 v112, 3, v2
	v_mul_u32_u24_e32 v114, 7, v163
	v_sub_u32_e32 v112, v112, v114
	v_mov_b32_e32 v113, 0
.Lpx_top:
	s_add_u32 s45, s44, s40
	s_cmp_gt_u32 s45, 0x1000000
	s_cbranch_scc1 .Lpx_rem
	v_lshl_add_u64 v[108:109], v[112:113], 4, s[8:9]
	v_lshl_add_u64 v[110:111], v[112:113], 3, s[24:25]
	global_load_dwordx4 v[124:127], v[108:109], off
	v_lshl_add_u64 v[108:109], s[38:39], 0, v[108:109]
	global_load_dwordx4 v[128:131], v[108:109], off
	v_lshl_add_u64 v[108:109], s[38:39], 0, v[108:109]
	global_load_dwordx4 v[132:135], v[108:109], off
	v_lshl_add_u64 v[108:109], s[38:39], 0, v[108:109]
	global_load_dwordx4 v[136:139], v[108:109], off
	v_lshl_add_u64 v[108:109], s[38:39], 0, v[108:109]
	global_load_dwordx4 v[140:143], v[108:109], off
	v_lshl_add_u64 v[108:109], s[38:39], 0, v[108:109]
	global_load_dwordx4 v[144:147], v[108:109], off
	v_lshl_add_u64 v[108:109], s[38:39], 0, v[108:109]
	global_load_dwordx4 v[148:151], v[108:109], off
	v_lshl_add_u64 v[108:109], s[38:39], 0, v[108:109]
	global_load_dwordx4 v[152:155], v[108:109], off
	s_waitcnt vmcnt(7)
	v_cvt_pk_bf16_f32 v124, v124, v125
	v_cvt_pk_bf16_f32 v125, v126, v127
	global_store_dwordx2 v[110:111], v[124:125], off
	v_lshl_add_u64 v[110:111], s[46:47], 0, v[110:111]
	s_waitcnt vmcnt(7)
	v_cvt_pk_bf16_f32 v128, v128, v129
	v_cvt_pk_bf16_f32 v129, v130, v131
	global_store_dwordx2 v[110:111], v[128:129], off
	v_lshl_add_u64 v[110:111], s[46:47], 0, v[110:111]
	s_waitcnt vmcnt(7)
	v_cvt_pk_bf16_f32 v132, v132, v133
	v_cvt_pk_bf16_f32 v133, v134, v135
	global_store_dwordx2 v[110:111], v[132:133], off
	v_lshl_add_u64 v[110:111], s[46:47], 0, v[110:111]
	s_waitcnt vmcnt(7)
	v_cvt_pk_bf16_f32 v136, v136, v137
	v_cvt_pk_bf16_f32 v137, v138, v139
	global_store_dwordx2 v[110:111], v[136:137], off
	v_lshl_add_u64 v[110:111], s[46:47], 0, v[110:111]
	s_waitcnt vmcnt(7)
	v_cvt_pk_bf16_f32 v140, v140, v141
	v_cvt_pk_bf16_f32 v141, v142, v143
	global_store_dwordx2 v[110:111], v[140:141], off
	v_lshl_add_u64 v[110:111], s[46:47], 0, v[110:111]
	s_waitcnt vmcnt(7)
	v_cvt_pk_bf16_f32 v144, v144, v145
	v_cvt_pk_bf16_f32 v145, v146, v147
	global_store_dwordx2 v[110:111], v[144:145], off
	v_lshl_add_u64 v[110:111], s[46:47], 0, v[110:111]
	s_waitcnt vmcnt(7)
	v_cvt_pk_bf16_f32 v148, v148, v149
	v_cvt_pk_bf16_f32 v149, v150, v151
	global_store_dwordx2 v[110:111], v[148:149], off
	v_lshl_add_u64 v[110:111], s[46:47], 0, v[110:111]
	s_waitcnt vmcnt(7)
	v_cvt_pk_bf16_f32 v152, v152, v153
	v_cvt_pk_bf16_f32 v153, v154, v155
	global_store_dwordx2 v[110:111], v[152:153], off
	s_mov_b32 s44, s45
	v_lshl_add_u64 v[2:3], s[40:41], 0, v[2:3]
	v_lshl_add_u64 v[112:113], s[40:41], 0, v[112:113]
	s_branch .Lpx_top
.Lpx_rem:
	v_cmp_lt_u64_e32 vcc, s[14:15], v[2:3]
	s_or_b64 s[4:5], vcc, s[4:5]
	s_andn2_b64 exec, exec, s[4:5]
	s_cbranch_execz .LBB0_97

; DEV int otid() { int t = threadIdx.x; asm volatile("" : "+v"(t)); return t; }
; DEV int obid() { int t = __builtin_amdgcn_readfirstlane(*(volatile int*)(smem_g + 147456 + 8)); asm volatile("" : "+s"(t)); return t; }
; DEV int onb() { int t = gridDim.x; asm volatile("" : "+s"(t)); return t; }
; DEV void store4(bf16_t* p, f32x4 v) { *(u32x2*)p = (u32x2){pk_bf16(v[0], v[1]), pk_bf16(v[2], v[3])}; }
; DEV void phase_prologue(const Params& p, char* smem) {
;     ...
;     {
;         const size_t n4 = (size_t)8192 * 1024 / 4; bf16_t* mb = (bf16_t*)(ws + OFF_MEMB);
;         for (size_t i = (size_t)obid() * NTHR + otid(); i < n4; i += (size_t)onb() * NTHR) { const f32x4 v = *(const f32x4*)(p.mem + i * 4); store4(mb + i * 4, v); }
;     }
.LBB0_97:
	s_or_b64 exec, exec, s[2:3]
	s_mov_b64 s[2:3], src_shared_base
	s_cmp_lg_u32 s0, -1
	s_cselect_b32 s2, s0, 0
	s_cselect_b32 s3, s3, 0
	v_mov_b32_e32 v2, s2
	v_mov_b32_e32 v3, s3
	flat_load_dword v1, v[2:3] sc0 sc1
	s_waitcnt vmcnt(0)
	v_mov_b32_e32 v2, v163
	v_readlane_b32 s52, v243, 2
	v_readlane_b32 s54, v243, 0
	v_readlane_b32 s53, v243, 3
	v_readlane_b32 s55, v243, 1
	s_waitcnt lgkmcnt(0)
	v_readfirstlane_b32 s2, v1
	s_ashr_i32 s3, s2, 31
	s_lshl_b64 s[2:3], s[2:3], 9
	v_ashrrev_i32_e32 v3, 31, v2
	v_lshl_add_u64 v[2:3], s[2:3], 0, v[2:3]
	s_mov_b64 s[2:3], 0x200000
	v_cmp_gt_u64_e32 vcc, s[2:3], v[2:3]
	s_and_saveexec_b64 s[2:3], vcc
	s_cbranch_execz .LBB0_100
	s_load_dword s14, s[6:7], 0x10
	s_add_u32 s4, s26, 0x1d30000
	s_addc_u32 s5, s27, 0
	s_mov_b64 s[8:9], 0
	s_waitcnt lgkmcnt(0)
	s_lshr_b32 s14, s14, 16
	s_cmp_lg_u32 s14, 0
	s_cselect_b64 s[14:15], -1, 0
	s_cmp_lg_u64 s[14:15], 0
	s_addc_u32 s16, s50, 0
	s_mov_b64 s[14:15], 0x1fffff
	s_lshl_b32 s40, s16, 12
	s_mov_b32 s41, 0
	s_mov_b64 s[38:39], 0x2000
	s_mov_b64 s[46:47], 0x1000
	s_mov_b32 s44, 0
	v_lshlrev_b32_e32 v112, 3, v2
	v_mul_u32_u24_e32 v114, 7, v163
	v_sub_u32_e32 v112, v112, v114
	v_mov_b32_e32 v113, 0
.Lpmem_top:
	s_add_u32 s45, s44, s40
	s_cmp_gt_u32 s45, 0x200000
	s_cbranch_scc1 .Lpmem_rem
	v_lshl_add_u64 v[108:109], v[112:113], 4, s[10:11]
	v_lshl_add_u64 v[110:111], v[112:113], 3, s[4:5]
	global_load_dwordx4 v[124:127], v[108:109], off
	v_lshl_add_u64 v[108:109], s[38:39], 0, v[108:109]
	global_load_dwordx4 v[128:131], v[108:109], off
	v_lshl_add_u64 v[108:109], s[38:39], 0, v[108:109]
	global_load_dwordx4 v[132:135], v[108:109], off
	v_lshl_add_u64 v[108:109], s[38:39], 0, v[108:109]
	global_load_dwordx4 v[136:139], v[108:109], off
	v_lshl_add_u64 v[108:109], s[38:39], 0, v[108:109]
	global_load_dwordx4 v[140:143], v[108:109], off
	v_lshl_add_u64 v[108:109], s[38:39], 0, v[108:109]
	global_load_dwordx4 v[144:147], v[108:109], off
	v_lshl_add_u64 v[108:109], s[38:39], 0, v[108:109]
	global_load_dwordx4 v[148:151], v[108:109], off
	v_lshl_add_u64 v[108:109], s[38:39], 0, v[108:109]
	global_load_dwordx4 v[152:155], v[108:109], off
	s_waitcnt vmcnt(7)
	v_cvt_pk_bf16_f32 v124, v124, v125
	v_cvt_pk_bf16_f32 v125, v126, v127
	global_store_dwordx2 v[110:111], v[124:125], off
	v_lshl_add_u64 v[110:111], s[46:47], 0, v[110:111]
	s_waitcnt vmcnt(7)
	v_cvt_pk_bf16_f32 v128, v128, v129
	v_cvt_pk_bf16_f32 v129, v130, v131
	global_store_dwordx2 v[110:111], v[128:129], off
	v_lshl_add_u64 v[110:111], s[46:47], 0, v[110:111]
	s_waitcnt vmcnt(7)
	v_cvt_pk_bf16_f32 v132, v132, v133
	v_cvt_pk_bf16_f32 v133, v134, v135
	global_store_dwordx2 v[110:111], v[132:133], off
	v_lshl_add_u64 v[110:111], s[46:47], 0, v[110:111]
	s_waitcnt vmcnt(7)
	v_cvt_pk_bf16_f32 v136, v136, v137
	v_cvt_pk_bf16_f32 v137, v138, v139
	global_store_dwordx2 v[110:111], v[136:137], off
	v_lshl_add_u64 v[110:111], s[46:47], 0, v[110:111]
	s_waitcnt vmcnt(7)
	v_cvt_pk_bf16_f32 v140, v140, v141
	v_cvt_pk_bf16_f32 v141, v142, v143
	global_store_dwordx2 v[110:111], v[140:141], off
	v_lshl_add_u64 v[110:111], s[46:47], 0, v[110:111]
	s_waitcnt vmcnt(7)
	v_cvt_pk_bf16_f32 v144, v144, v145
	v_cvt_pk_bf16_f32 v145, v146, v147
	global_store_dwordx2 v[110:111], v[144:145], off
	v_lshl_add_u64 v[110:111], s[46:47], 0, v[110:111]
	s_waitcnt vmcnt(7)
	v_cvt_pk_bf16_f32 v148, v148, v149
	v_cvt_pk_bf16_f32 v149, v150, v151
	global_store_dwordx2 v[110:111], v[148:149], off
	v_lshl_add_u64 v[110:111], s[46:47], 0, v[110:111]
	s_waitcnt vmcnt(7)
	v_cvt_pk_bf16_f32 v152, v152, v153
	v_cvt_pk_bf16_f32 v153, v154, v155
	global_store_dwordx2 v[110:111], v[152:153], off
	s_mov_b32 s44, s45
	v_lshl_add_u64 v[2:3], s[40:41], 0, v[2:3]
	v_lshl_add_u64 v[112:113], s[40:41], 0, v[112:113]
	s_branch .Lpmem_top
.Lpmem_rem:
	v_cmp_lt_u64_e32 vcc, s[14:15], v[2:3]
	s_or_b64 s[8:9], vcc, s[8:9]
	s_andn2_b64 exec, exec, s[8:9]
	s_cbranch_execz .LBB0_100

; #define STAGE(stg, kt) do { char* _l = l0 + (stg) * 32768; int _k = (kt) + rot; _k = _k >= nk ? _k - nk : _k; _k *= 32; glds16(gA + _k, _l); glds16(gA + hA + _k, _l + 8192); glds16(gB + _k, _l + 16384); glds16(gB + hB + _k, _l + 24576); } while (0)
;     ...
;     int R, C; { const int b = tid * 16, st = b >> 10, sb = b & 1023, swz = sb ^ (((sb >> 9) & 1) << 5); R = st * 16 + (swz >> 6); C = (swz & 63) >> 1; }
;     const bf16_t* gA = A + (size_t)(m0 + R) * lda + C;
;     const bf16_t* gB = Bt + (size_t)(n0 + R) * ldb + C;
;     const size_t hA = (size_t)128 * lda, hB = (size_t)128 * ldb;
;     char* l0 = smem + tid * 16;
;     const int sw = (fr * 64 + fq * 16) ^ ((fr >> 3) << 5);
;     const char* rdA = smem + (wr * 4) * 1024 + sw;
;     const char* rdB = smem + 16384 + wc * 8192 + sw;
;     const int nk = K / 32;
;     ...
;     __syncthreads();
;     STAGE(0, 0); STAGE(1, 1); STAGE(2, 2); STAGE(3, 3);
; DEV void phase1(const Params& p, int l, char* smem) {
;     ...
;             const int xcd = it & 7, w = it >> 3;
;             const int g = w >> 5, within = w & 31, mtg = g / 6, ntg = g % 6;
;             const int mt = xcd * 32 + mtg * 8 + (within >> 2), nt = ntg * 4 + (within & 3);
;             gemm256(acc, xb, 1024, mt * 256, win, 1024, nt * 256, 1024, smem, ((within & 3) * 8 + (within >> 2)) & 31);
.LBB0_155:
	s_andn2_b64 vcc, exec, s[0:1]
	s_cbranch_vccnz .LBB0_124
	s_ashr_i32 s5, s46, 8
	s_mul_hi_i32 s6, s5, 0x2aaaaaab
	s_lshr_b32 s8, s6, 31
	s_add_i32 s6, s6, s8
	s_mul_i32 s8, s6, 6
	s_sub_i32 s5, s5, s8
	s_lshl_b32 s8, s46, 5
	s_bfe_u32 s1, s46, 0x20003
	s_and_b32 s8, s8, 0xe0
	s_lshl_b32 s6, s6, 3
	s_bfe_u32 s0, s46, 0x30005
	s_lshl_b32 s4, s1, 3
	s_add_i32 s6, s6, s8
	v_mov_b32_e32 v2, v163
	s_add_i32 s7, s1, s0
	s_or_b32 s0, s6, s0
	s_lshl_b32 s66, s0, 8
	v_ashrrev_i32_e32 v1, 2, v2
	v_lshrrev_b32_e32 v6, 2, v2
	v_lshlrev_b32_e32 v5, 4, v2
	v_and_b32_e32 v0, 32, v2
	v_bfi_b32 v6, 15, v6, v1
	v_bitop3_b32 v160, v5, v0, 48 bitop3:0x6c
	v_add_u32_e32 v0, s66, v6
	v_ashrrev_i32_e32 v1, 31, v0
	s_lshl_b32 s0, s5, 10
	s_lshl_b32 s1, s1, 8
	v_lshlrev_b64 v[0:1], 11, v[0:1]
	s_or_b32 s5, s0, s1
	v_lshl_add_u64 v[0:1], s[2:3], 0, v[0:1]
	v_lshl_add_u64 v[166:167], v[0:1], 0, v[160:161]
	v_add_u32_e32 v0, s5, v6
	v_ashrrev_i32_e32 v1, 31, v0
	v_lshlrev_b64 v[0:1], 11, v[0:1]
	v_lshl_add_u64 v[0:1], s[38:39], 0, v[0:1]
	v_and_b32_e32 v3, 15, v2
	v_lshl_add_u64 v[168:169], v[0:1], 0, v[160:161]
	v_lshlrev_b32_e32 v1, 2, v2
	v_and_b32_e32 v4, 48, v2
	v_lshlrev_b32_e32 v0, 6, v3
	v_and_b32_e32 v1, 32, v1
	v_bitop3_b32 v0, v0, v1, v4 bitop3:0x36
	v_lshlrev_b32_e32 v1, 5, v2
	v_and_b32_e32 v1, 0xfffff000, v1
	v_add_u32_e32 v160, 0, v5
	v_add3_u32 v165, 0, v1, v0
	v_lshlrev_b32_e32 v1, 7, v2
	v_and_b32_e32 v1, 0x2000, v1
	s_lshl_b32 s10, s7, 6
	v_readfirstlane_b32 s0, v160
	v_add_u32_e32 v2, 0x2000, v160
	v_add3_u32 v174, 0, v1, v0
	v_lshl_add_u64 v[0:1], v[166:167], 0, s[10:11]
	s_mov_b32 m0, s0
	v_lshl_add_u64 v[170:171], v[166:167], 0, s[12:13]
	v_readfirstlane_b32 s0, v2
	v_add_u32_e32 v2, 0x4000, v160
	s_add_i32 s4, s7, 4
	s_waitcnt vmcnt(0)
	s_barrier
	global_load_lds_dwordx4 v[0:1], off
	v_lshl_add_u64 v[0:1], v[170:171], 0, s[10:11]
	s_mov_b32 m0, s0
	v_readfirstlane_b32 s0, v2
	v_add_u32_e32 v2, 0x6000, v160
	global_load_lds_dwordx4 v[0:1], off
	v_lshl_add_u64 v[0:1], v[168:169], 0, s[10:11]
	s_mov_b32 m0, s0
	v_readfirstlane_b32 s0, v2
	s_cmp_eq_u32 s7, 31
	global_load_lds_dwordx4 v[0:1], off
	s_mov_b32 m0, s0
	s_cselect_b32 s0, 0xffffffe0, 0
	s_or_b32 s0, s7, s0
	s_lshl_b32 s0, s0, 5
	s_add_i32 s0, s0, 32
	v_lshl_add_u64 v[172:173], v[168:169], 0, s[12:13]
	v_add_u32_e32 v2, 0x8000, v160
	s_ashr_i32 s1, s0, 31
	v_lshl_add_u64 v[0:1], v[172:173], 0, s[10:11]
	s_lshl_b64 s[0:1], s[0:1], 1
	v_readfirstlane_b32 s8, v2
	v_add_u32_e32 v2, 0xa000, v160
	global_load_lds_dwordx4 v[0:1], off
	v_lshl_add_u64 v[0:1], v[166:167], 0, s[0:1]
	s_mov_b32 m0, s8
	v_readfirstlane_b32 s8, v2
	v_add_u32_e32 v2, 0xc000, v160
	global_load_lds_dwordx4 v[0:1], off
	v_lshl_add_u64 v[0:1], v[170:171], 0, s[0:1]
	s_mov_b32 m0, s8
	v_readfirstlane_b32 s8, v2
	global_load_lds_dwordx4 v[0:1], off
	v_lshl_add_u64 v[0:1], v[168:169], 0, s[0:1]
	s_mov_b32 m0, s8
	v_add_u32_e32 v2, 0xe000, v160
	global_load_lds_dwordx4 v[0:1], off
	v_lshl_add_u64 v[0:1], v[172:173], 0, s[0:1]
	v_readfirstlane_b32 s0, v2
	s_cmp_lt_u32 s7, 30
	s_mov_b32 m0, s0
	s_cselect_b32 s0, 0, 0xffffffe0
	s_or_b32 s0, s7, s0
	s_lshl_b32 s0, s0, 5
	s_add_i32 s0, s0, 64
	v_add_u32_e32 v2, 0x10000, v160
	s_ashr_i32 s1, s0, 31
	s_lshl_b64 s[0:1], s[0:1], 1
	v_readfirstlane_b32 s8, v2
	v_add_u32_e32 v2, 0x12000, v160
	global_load_lds_dwordx4 v[0:1], off
	v_lshl_add_u64 v[0:1], v[166:167], 0, s[0:1]
	s_mov_b32 m0, s8
	v_readfirstlane_b32 s8, v2
	v_add_u32_e32 v2, 0x14000, v160
	global_load_lds_dwordx4 v[0:1], off
	v_lshl_add_u64 v[0:1], v[170:171], 0, s[0:1]
	s_mov_b32 m0, s8
	v_readfirstlane_b32 s8, v2
	global_load_lds_dwordx4 v[0:1], off
	v_lshl_add_u64 v[0:1], v[168:169], 0, s[0:1]
	s_mov_b32 m0, s8
	v_add_u32_e32 v2, 0x16000, v160
	global_load_lds_dwordx4 v[0:1], off
	v_lshl_add_u64 v[0:1], v[172:173], 0, s[0:1]
	v_readfirstlane_b32 s0, v2
	s_cmp_lt_u32 s7, 29
	s_mov_b32 m0, s0
	s_cselect_b32 s0, 0, 0xffffffe0
	s_or_b32 s0, s7, s0
	s_lshl_b32 s0, s0, 5
	s_addk_i32 s0, 0x60
	v_add_u32_e32 v2, 0x18000, v160
	s_ashr_i32 s1, s0, 31
	s_lshl_b64 s[0:1], s[0:1], 1
	v_readfirstlane_b32 s7, v2
	v_add_u32_e32 v2, 0x1a000, v160
	global_load_lds_dwordx4 v[0:1], off
	v_lshl_add_u64 v[0:1], v[166:167], 0, s[0:1]
	s_mov_b32 m0, s7
	v_readfirstlane_b32 s7, v2
	v_add_u32_e32 v2, 0x1c000, v160
	global_load_lds_dwordx4 v[0:1], off
	v_lshl_add_u64 v[0:1], v[170:171], 0, s[0:1]
	s_mov_b32 m0, s7
	v_readfirstlane_b32 s7, v2
	global_load_lds_dwordx4 v[0:1], off
	v_lshl_add_u64 v[0:1], v[168:169], 0, s[0:1]
	s_mov_b32 m0, s7
	v_add_u32_e32 v2, 0x1e000, v160
	global_load_lds_dwordx4 v[0:1], off
	v_lshl_add_u64 v[0:1], v[172:173], 0, s[0:1]
	v_readfirstlane_b32 s0, v2
	s_mov_b32 m0, s0
	s_mov_b32 s6, 0
	global_load_lds_dwordx4 v[0:1], off
	s_waitcnt vmcnt(12)
	s_barrier
; DEV void zero_acc8(f32x4 (&acc)[4][8]) {
; #pragma unroll
;     for (int mi = 0; mi < 4; ++mi)
; #pragma unroll
;         for (int ni = 0; ni < 8; ++ni) acc[mi][ni] = (f32x4){0.f, 0.f, 0.f, 0.f};
; }
	v_mov_b32_e32 v0, 0
	s_mov_b32 s7, 0
	v_mov_b32_e32 v1, v0
	v_mov_b32_e32 v2, v0
	v_mov_b32_e32 v3, v0
	v_mov_b32_e32 v4, v0
	v_mov_b32_e32 v5, v0
	v_mov_b32_e32 v6, v0
	v_mov_b32_e32 v7, v0
	v_mov_b32_e32 v8, v0
	v_mov_b32_e32 v9, v0
	v_mov_b32_e32 v10, v0
	v_mov_b32_e32 v11, v0
	v_mov_b32_e32 v12, v0
	v_mov_b32_e32 v13, v0
	v_mov_b32_e32 v14, v0
	v_mov_b32_e32 v15, v0
	v_mov_b32_e32 v16, v0
	v_mov_b32_e32 v17, v0
	v_mov_b32_e32 v18, v0
	v_mov_b32_e32 v19, v0
	v_mov_b32_e32 v20, v0
	v_mov_b32_e32 v21, v0
	v_mov_b32_e32 v22, v0
	v_mov_b32_e32 v23, v0
	v_mov_b32_e32 v24, v0
	v_mov_b32_e32 v25, v0
	v_mov_b32_e32 v26, v0
	v_mov_b32_e32 v27, v0
	v_mov_b32_e32 v28, v0
	v_mov_b32_e32 v29, v0
	v_mov_b32_e32 v30, v0
	v_mov_b32_e32 v31, v0
	v_mov_b32_e32 v32, v0
	v_mov_b32_e32 v33, v0
	v_mov_b32_e32 v34, v0
	v_mov_b32_e32 v35, v0
	v_mov_b32_e32 v36, v0
	v_mov_b32_e32 v37, v0
	v_mov_b32_e32 v38, v0
	v_mov_b32_e32 v39, v0
	v_mov_b32_e32 v40, v0
	v_mov_b32_e32 v41, v0
	v_mov_b32_e32 v42, v0
	v_mov_b32_e32 v43, v0
	v_mov_b32_e32 v44, v0
	v_mov_b32_e32 v45, v0
	v_mov_b32_e32 v46, v0
	v_mov_b32_e32 v47, v0
	v_mov_b32_e32 v48, v0
	v_mov_b32_e32 v49, v0
	v_mov_b32_e32 v50, v0
	v_mov_b32_e32 v51, v0
	v_mov_b32_e32 v52, v0
	v_mov_b32_e32 v53, v0
	v_mov_b32_e32 v54, v0
	v_mov_b32_e32 v55, v0
	v_mov_b32_e32 v56, v0
	v_mov_b32_e32 v57, v0
	v_mov_b32_e32 v58, v0
	v_mov_b32_e32 v59, v0
	v_mov_b32_e32 v60, v0
	v_mov_b32_e32 v61, v0
	v_mov_b32_e32 v62, v0
	v_mov_b32_e32 v63, v0
	v_mov_b32_e32 v64, v0
	v_mov_b32_e32 v65, v0
	v_mov_b32_e32 v66, v0
	v_mov_b32_e32 v67, v0
	v_mov_b32_e32 v68, v0
	v_mov_b32_e32 v69, v0
	v_mov_b32_e32 v70, v0
	v_mov_b32_e32 v71, v0
	v_mov_b32_e32 v72, v0
	v_mov_b32_e32 v73, v0
	v_mov_b32_e32 v74, v0
	v_mov_b32_e32 v75, v0
	v_mov_b32_e32 v76, v0
	v_mov_b32_e32 v77, v0
	v_mov_b32_e32 v78, v0
	v_mov_b32_e32 v79, v0
	v_mov_b32_e32 v80, v0
	v_mov_b32_e32 v81, v0
	v_mov_b32_e32 v82, v0
	v_mov_b32_e32 v83, v0
	v_mov_b32_e32 v84, v0
	v_mov_b32_e32 v85, v0
	v_mov_b32_e32 v86, v0
	v_mov_b32_e32 v87, v0
	v_mov_b32_e32 v88, v0
	v_mov_b32_e32 v89, v0
	v_mov_b32_e32 v90, v0
	v_mov_b32_e32 v91, v0
	v_mov_b32_e32 v92, v0
	v_mov_b32_e32 v93, v0
	v_mov_b32_e32 v94, v0
	v_mov_b32_e32 v95, v0
	v_mov_b32_e32 v96, v0
	v_mov_b32_e32 v97, v0
	v_mov_b32_e32 v98, v0
	v_mov_b32_e32 v99, v0
	v_mov_b32_e32 v100, v0
	v_mov_b32_e32 v101, v0
	v_mov_b32_e32 v102, v0
	v_mov_b32_e32 v103, v0
	v_mov_b32_e32 v104, v0
	v_mov_b32_e32 v105, v0
	v_mov_b32_e32 v106, v0
	v_mov_b32_e32 v107, v0
	v_mov_b32_e32 v108, v0
	v_mov_b32_e32 v109, v0
	v_mov_b32_e32 v110, v0
	v_mov_b32_e32 v111, v0
	v_mov_b32_e32 v112, v0
	v_mov_b32_e32 v113, v0
	v_mov_b32_e32 v114, v0
	v_mov_b32_e32 v115, v0
	v_mov_b32_e32 v116, v0
	v_mov_b32_e32 v117, v0
	v_mov_b32_e32 v118, v0
	v_mov_b32_e32 v119, v0
	v_mov_b32_e32 v120, v0
	v_mov_b32_e32 v121, v0
	v_mov_b32_e32 v122, v0
	v_mov_b32_e32 v123, v0
	v_mov_b32_e32 v124, v0
	v_mov_b32_e32 v125, v0
	v_mov_b32_e32 v126, v0
	v_mov_b32_e32 v127, v0
	s_branch .LBB0_158

; DEV unsigned pk_bf16(float lo, float hi) { const bf16x2_t v = __builtin_convertvector((f32x2){lo, hi}, bf16x2_t); return __builtin_bit_cast(unsigned, v); }
;     ...
;             float ps = 0.f;
; #pragma unroll
;             for (int ni = 0; ni < 4; ++ni)
; #pragma unroll
;                 for (int r = 0; r < 4; ++r) { const float pv = __builtin_amdgcn_exp2f(__builtin_fmaf(s[mi][ni][r], scale_log2, -mc)); s[mi][ni][r] = pv; ps += pv; }
;             if (__builtin_amdgcn_ballot_w64(mnew > mrun[mi]) != 0ull) {
;                 const float alpha = __builtin_amdgcn_exp2f((mrun[mi] - mnew) * scale_log2);
;                 lrun[mi] *= alpha;
; #pragma unroll
;                 for (int di = 0; di < DV / 16; ++di) o[mi][di] *= alpha;
;             }
;             mrun[mi] = mnew;
;             lrun[mi] += ps;
; #pragma unroll
;             for (int s2 = 0; s2 < 2; ++s2) { const f32x4 a = s[mi][2 * s2], b = s[mi][2 * s2 + 1];
;                 const u32x4 pk = (u32x4){pk_bf16(a[0], a[1]), pk_bf16(a[2], a[3]), pk_bf16(b[0], b[1]), pk_bf16(b[2], b[3])};
;                 pf[mi][s2] = __builtin_bit_cast(bf16x8, pk); }
;         }
; #pragma unroll
;         for (int di = 0; di < DV / 16; ++di)
; #pragma unroll
;             for (int s2 = 0; s2 < 2; ++s2) {
;                 const u32x2 v0 = *(const u32x2*)(cV + (di * 16 + fr) * LDV + s2 * 32 + fq * 4), v1 = *(const u32x2*)(cV + (di * 16 + fr) * LDV + s2 * 32 + 16 + fq * 4);
;                 const bf16x8 vf = __builtin_bit_cast(bf16x8, ((u32x4){v0[0], v0[1], v1[0], v1[1]}));
; #pragma unroll
;                 for (int mi = 0; mi < MIA; ++mi) o[mi][di] = __builtin_amdgcn_mfma_f32_16x16x32_bf16(vf, pf[mi][s2], o[mi][di], 0, 0, 0);
;             }
.LBB0_350:
	v_mul_f32_e32 v48, 0xbe0293ee, v48
	v_fmamk_f32 v12, v12, 0x3e0293ee, v48
	v_exp_f32_e32 v12, v12
	v_fmamk_f32 v13, v13, 0x3e0293ee, v48
	v_exp_f32_e32 v13, v13
	v_fmamk_f32 v14, v14, 0x3e0293ee, v48
	v_exp_f32_e32 v14, v14
	v_fmamk_f32 v15, v15, 0x3e0293ee, v48
	v_exp_f32_e32 v15, v15
	v_fmamk_f32 v32, v32, 0x3e0293ee, v48
	v_add_f32_e32 v49, 0, v12
	v_exp_f32_e32 v32, v32
	v_fmamk_f32 v33, v33, 0x3e0293ee, v48
	v_add_f32_e32 v49, v13, v49
	v_exp_f32_e32 v33, v33
	v_fmamk_f32 v34, v34, 0x3e0293ee, v48
	v_add_f32_e32 v49, v14, v49
	v_exp_f32_e32 v34, v34
	v_fmamk_f32 v35, v35, 0x3e0293ee, v48
	v_add_f32_e32 v49, v15, v49
	v_exp_f32_e32 v35, v35
	v_fmamk_f32 v8, v8, 0x3e0293ee, v48
	v_add_f32_e32 v49, v32, v49
	v_exp_f32_e32 v8, v8
	v_fmamk_f32 v9, v9, 0x3e0293ee, v48
	v_add_f32_e32 v49, v33, v49
	v_exp_f32_e32 v9, v9
	v_fmamk_f32 v10, v10, 0x3e0293ee, v48
	v_add_f32_e32 v49, v34, v49
	v_exp_f32_e32 v10, v10
	v_fmamk_f32 v11, v11, 0x3e0293ee, v48
	v_add_f32_e32 v49, v35, v49
	v_exp_f32_e32 v11, v11
	v_fmamk_f32 v4, v4, 0x3e0293ee, v48
	v_add_f32_e32 v49, v8, v49
	v_exp_f32_e32 v4, v4
	v_fmamk_f32 v5, v5, 0x3e0293ee, v48
	v_add_f32_e32 v49, v9, v49
	v_exp_f32_e32 v5, v5
	v_fmamk_f32 v6, v6, 0x3e0293ee, v48
	v_add_f32_e32 v49, v10, v49
	v_exp_f32_e32 v6, v6
	v_fmac_f32_e32 v48, 0x3e0293ee, v7
	v_add_f32_e32 v49, v11, v49
	v_exp_f32_e32 v7, v48
	v_add_f32_e32 v49, v4, v49
	v_add_f32_e32 v49, v5, v49
	v_add_f32_e32 v49, v6, v49
	v_add_f32_e32 v53, v7, v49
	v_cvt_pk_bf16_f32 v60, v4, v5
	v_cvt_pk_bf16_f32 v61, v6, v7
	ds_read2_b64 v[4:7], v85 offset1:4
	v_cvt_pk_bf16_f32 v58, v8, v9
	v_cvt_pk_bf16_f32 v59, v10, v11
	ds_read2_b64 v[8:11], v85 offset0:8 offset1:12
	v_cvt_pk_bf16_f32 v54, v12, v13
	v_cvt_pk_bf16_f32 v55, v14, v15
	v_cvt_pk_bf16_f32 v56, v32, v33
	v_cvt_pk_bf16_f32 v57, v34, v35
	s_lshl_b64 s[0:1], s[2:3], 12
	s_add_u32 s0, s46, s0
	s_waitcnt lgkmcnt(1)
	v_mfma_f32_16x16x32_bf16 v[4:7], v[4:7], v[54:57], v[16:19]
	s_addc_u32 s1, s47, s1
	s_add_u32 s0, s0, s65
	s_addc_u32 s1, s1, 0
	s_waitcnt lgkmcnt(0)
	v_mfma_f32_16x16x32_bf16 v[48:51], v[8:11], v[58:61], v[4:7]
	v_add_u32_e32 v8, 0x4800, v93
	s_add_i32 s45, s45, s18
	s_add_i32 s28, s28, s29
	ds_read2_b64 v[4:7], v8 offset1:4
	ds_read2_b64 v[8:11], v8 offset0:8 offset1:12
	s_waitcnt lgkmcnt(1)
	v_mfma_f32_16x16x32_bf16 v[4:7], v[4:7], v[54:57], v[20:23]
	s_add_i32 s36, s36, s37
	s_cmpk_gt_i32 s45, 0x7ff
	s_waitcnt lgkmcnt(0)
	v_mfma_f32_16x16x32_bf16 v[32:35], v[8:11], v[58:61], v[4:7]
	v_add_u32_e32 v8, 0x4800, v92
	s_nop 2
	ds_read2_b64 v[4:7], v8 offset1:4
	ds_read2_b64 v[8:11], v8 offset0:8 offset1:12
	s_waitcnt lgkmcnt(1)
	v_mfma_f32_16x16x32_bf16 v[4:7], v[4:7], v[54:57], v[24:27]
	s_nop 2
	ds_read2_b64 v[24:27], v88 offset0:200 offset1:204
	s_waitcnt lgkmcnt(1)
	v_mfma_f32_16x16x32_bf16 v[20:23], v[8:11], v[58:61], v[4:7]
	v_add_u32_e32 v8, 0x4800, v91
	s_nop 1
	ds_read2_b64 v[4:7], v8 offset1:4
	ds_read2_b64 v[8:11], v8 offset0:8 offset1:12
	s_waitcnt lgkmcnt(1)
	v_mfma_f32_16x16x32_bf16 v[4:7], v[4:7], v[54:57], v[28:31]
	s_waitcnt lgkmcnt(0)
	v_mfma_f32_16x16x32_bf16 v[16:19], v[8:11], v[58:61], v[4:7]
	ds_read2_b64 v[8:11], v86 offset0:136 offset1:140
	s_nop 4
	ds_read2_b64 v[4:7], v86 offset0:128 offset1:132
	s_waitcnt lgkmcnt(0)
	v_mfma_f32_16x16x32_bf16 v[4:7], v[4:7], v[54:57], v[36:39]
	v_mfma_f32_16x16x32_bf16 v[12:15], v[8:11], v[58:61], v[4:7]
	ds_read2_b64 v[8:11], v87 offset0:168 offset1:172
	s_nop 5
	ds_read2_b64 v[4:7], v87 offset0:160 offset1:164
	s_waitcnt lgkmcnt(0)
	v_mfma_f32_16x16x32_bf16 v[4:7], v[4:7], v[54:57], v[44:47]
	v_mfma_f32_16x16x32_bf16 v[8:11], v[8:11], v[58:61], v[4:7]
	s_nop 6
	ds_read2_b64 v[4:7], v88 offset0:192 offset1:196
	s_waitcnt lgkmcnt(0)
	v_mfma_f32_16x16x32_bf16 v[4:7], v[4:7], v[54:57], v[40:43]
	v_mfma_f32_16x16x32_bf16 v[4:7], v[24:27], v[58:61], v[4:7]
	ds_read2_b64 v[24:27], v89 offset0:224 offset1:228
	s_waitcnt lgkmcnt(0)
	v_mfma_f32_16x16x32_bf16 v[0:3], v[24:27], v[54:57], v[0:3]
	ds_read2_b64 v[24:27], v89 offset0:232 offset1:236
	s_waitcnt lgkmcnt(0)
; DEV float bflo(unsigned u) { return __uint_as_float(u << 16); }
; DEV float bfhi(unsigned u) { return __uint_as_float(u & 0xffff0000u); }
; DEV void store4(bf16_t* p, f32x4 v) { *(u32x2*)p = (u32x2){pk_bf16(v[0], v[1]), pk_bf16(v[2], v[3])}; }
;     ...
; #pragma unroll
;     for (int mi = 0; mi < MIA; ++mi) {
;         float lt = lrun[mi]; lt += __shfl_xor(lt, 16); lt += __shfl_xor(lt, 32);
;         const float inv = __builtin_amdgcn_rcpf(lt);
;         bf16_t* yrow = Yp + (size_t)(w * 16 * MIA + mi * 16 + fr) * ldy;
; #pragma unroll
;         for (int di = 0; di < DV / 16; ++di) { bf16_t* yp = yrow + di * 16 + fq * 4; const u32x2 g = *(const u32x2*)yp;
;             f32x4 v = o[mi][di] * inv; v[0] *= bflo(g[0]); v[1] *= bfhi(g[0]); v[2] *= bflo(g[1]); v[3] *= bfhi(g[1]); if (!dry) store4(yp, v); }
;     }
	v_mfma_f32_16x16x32_bf16 v[0:3], v[24:27], v[58:61], v[0:3]
	v_lshlrev_b64 v[24:25], 12, v[80:81]
	v_lshl_add_u64 v[24:25], s[0:1], 0, v[24:25]
	v_lshl_add_u64 v[28:29], v[24:25], 0, v[160:161]
	s_mov_b64 s[0:1], 0x45b0c00
	v_lshl_add_u64 v[24:25], v[28:29], 0, s[0:1]
	global_load_dwordx2 v[104:105], v[24:25], off
	global_load_dwordx2 v[106:107], v[24:25], off offset:32
	global_load_dwordx2 v[108:109], v[24:25], off offset:64
	global_load_dwordx2 v[110:111], v[24:25], off offset:96
	global_load_dwordx2 v[112:113], v[24:25], off offset:128
	global_load_dwordx2 v[114:115], v[24:25], off offset:160
	global_load_dwordx2 v[116:117], v[24:25], off offset:192
	global_load_dwordx2 v[118:119], v[24:25], off offset:224
	v_add_f32_e32 v26, v53, v52
	ds_bpermute_b32 v27, v82, v26
	s_waitcnt lgkmcnt(0)
	v_add_f32_e32 v26, v26, v27
	ds_bpermute_b32 v27, v83, v26
	s_waitcnt lgkmcnt(0)
	v_add_f32_e32 v26, v26, v27
	v_rcp_f32_e32 v26, v26
	s_waitcnt vmcnt(0)
	v_lshlrev_b32_e32 v120, 16, v104
	v_and_b32_e32 v121, 0xffff0000, v104
	v_lshlrev_b32_e32 v122, 16, v105
	v_and_b32_e32 v123, 0xffff0000, v105
	v_pk_mul_f32 v[48:49], v[48:49], v[26:27] op_sel_hi:[1,0]
	v_pk_mul_f32 v[50:51], v[50:51], v[26:27] op_sel_hi:[1,0]
	v_pk_mul_f32 v[48:49], v[48:49], v[120:121]
	v_pk_mul_f32 v[50:51], v[50:51], v[122:123]
	v_cvt_pk_bf16_f32 v48, v48, v49
	v_cvt_pk_bf16_f32 v49, v50, v51
	global_store_dwordx2 v[24:25], v[48:49], off
	v_lshlrev_b32_e32 v120, 16, v106
	v_and_b32_e32 v121, 0xffff0000, v106
	v_lshlrev_b32_e32 v122, 16, v107
	v_and_b32_e32 v123, 0xffff0000, v107
	v_pk_mul_f32 v[32:33], v[32:33], v[26:27] op_sel_hi:[1,0]
	v_pk_mul_f32 v[34:35], v[34:35], v[26:27] op_sel_hi:[1,0]
	v_pk_mul_f32 v[32:33], v[32:33], v[120:121]
	v_pk_mul_f32 v[34:35], v[34:35], v[122:123]
	v_cvt_pk_bf16_f32 v32, v32, v33
	v_cvt_pk_bf16_f32 v33, v34, v35
	global_store_dwordx2 v[24:25], v[32:33], off offset:32
	v_lshlrev_b32_e32 v120, 16, v108
	v_and_b32_e32 v121, 0xffff0000, v108
	v_lshlrev_b32_e32 v122, 16, v109
	v_and_b32_e32 v123, 0xffff0000, v109
	v_pk_mul_f32 v[20:21], v[20:21], v[26:27] op_sel_hi:[1,0]
	v_pk_mul_f32 v[22:23], v[22:23], v[26:27] op_sel_hi:[1,0]
	v_pk_mul_f32 v[20:21], v[20:21], v[120:121]
	v_pk_mul_f32 v[22:23], v[22:23], v[122:123]
	v_cvt_pk_bf16_f32 v20, v20, v21
	v_cvt_pk_bf16_f32 v21, v22, v23
	global_store_dwordx2 v[24:25], v[20:21], off offset:64
	v_lshlrev_b32_e32 v120, 16, v110
	v_and_b32_e32 v121, 0xffff0000, v110
	v_lshlrev_b32_e32 v122, 16, v111
	v_and_b32_e32 v123, 0xffff0000, v111
	v_pk_mul_f32 v[16:17], v[16:17], v[26:27] op_sel_hi:[1,0]
	v_pk_mul_f32 v[18:19], v[18:19], v[26:27] op_sel_hi:[1,0]
	v_pk_mul_f32 v[16:17], v[16:17], v[120:121]
	v_pk_mul_f32 v[18:19], v[18:19], v[122:123]
	v_cvt_pk_bf16_f32 v16, v16, v17
	v_cvt_pk_bf16_f32 v17, v18, v19
	global_store_dwordx2 v[24:25], v[16:17], off offset:96
	v_lshlrev_b32_e32 v120, 16, v112
	v_and_b32_e32 v121, 0xffff0000, v112
	v_lshlrev_b32_e32 v122, 16, v113
	v_and_b32_e32 v123, 0xffff0000, v113
	v_pk_mul_f32 v[12:13], v[12:13], v[26:27] op_sel_hi:[1,0]
	v_pk_mul_f32 v[14:15], v[14:15], v[26:27] op_sel_hi:[1,0]
	v_pk_mul_f32 v[12:13], v[12:13], v[120:121]
	v_pk_mul_f32 v[14:15], v[14:15], v[122:123]
	v_cvt_pk_bf16_f32 v12, v12, v13
	v_cvt_pk_bf16_f32 v13, v14, v15
	global_store_dwordx2 v[24:25], v[12:13], off offset:128
	v_lshlrev_b32_e32 v120, 16, v114
	v_and_b32_e32 v121, 0xffff0000, v114
	v_lshlrev_b32_e32 v122, 16, v115
	v_and_b32_e32 v123, 0xffff0000, v115
	v_pk_mul_f32 v[8:9], v[8:9], v[26:27] op_sel_hi:[1,0]
	v_pk_mul_f32 v[10:11], v[10:11], v[26:27] op_sel_hi:[1,0]
	v_pk_mul_f32 v[8:9], v[8:9], v[120:121]
	v_pk_mul_f32 v[10:11], v[10:11], v[122:123]
	v_cvt_pk_bf16_f32 v8, v8, v9
	v_cvt_pk_bf16_f32 v9, v10, v11
	global_store_dwordx2 v[24:25], v[8:9], off offset:160
	v_lshlrev_b32_e32 v120, 16, v116
	v_and_b32_e32 v121, 0xffff0000, v116
	v_lshlrev_b32_e32 v122, 16, v117
	v_and_b32_e32 v123, 0xffff0000, v117
	v_pk_mul_f32 v[4:5], v[4:5], v[26:27] op_sel_hi:[1,0]
	v_pk_mul_f32 v[6:7], v[6:7], v[26:27] op_sel_hi:[1,0]
	v_pk_mul_f32 v[4:5], v[4:5], v[120:121]
	v_pk_mul_f32 v[6:7], v[6:7], v[122:123]
	v_cvt_pk_bf16_f32 v4, v4, v5
	v_cvt_pk_bf16_f32 v5, v6, v7
	global_store_dwordx2 v[24:25], v[4:5], off offset:192
	v_lshlrev_b32_e32 v120, 16, v118
	v_and_b32_e32 v121, 0xffff0000, v118
	v_lshlrev_b32_e32 v122, 16, v119
	v_and_b32_e32 v123, 0xffff0000, v119
	v_pk_mul_f32 v[0:1], v[0:1], v[26:27] op_sel_hi:[1,0]
	v_pk_mul_f32 v[2:3], v[2:3], v[26:27] op_sel_hi:[1,0]
	v_pk_mul_f32 v[0:1], v[0:1], v[120:121]
	v_pk_mul_f32 v[2:3], v[2:3], v[122:123]
	v_cvt_pk_bf16_f32 v0, v0, v1
	v_cvt_pk_bf16_f32 v1, v2, v3
	global_store_dwordx2 v[24:25], v[0:1], off offset:224
	s_cbranch_scc1 .LBB0_391

; DEV float bflo(unsigned u) { return __uint_as_float(u << 16); }
; DEV float bfhi(unsigned u) { return __uint_as_float(u & 0xffff0000u); }
; DEV void store4(bf16_t* p, f32x4 v) { *(u32x2*)p = (u32x2){pk_bf16(v[0], v[1]), pk_bf16(v[2], v[3])}; }
;     ...
; #pragma unroll
;     for (int mi = 0; mi < MIA; ++mi) {
;         float lt = lrun[mi]; lt += __shfl_xor(lt, 16); lt += __shfl_xor(lt, 32);
;         const float inv = __builtin_amdgcn_rcpf(lt);
;         bf16_t* yrow = Yp + (size_t)(w * 16 * MIA + mi * 16 + fr) * ldy;
; #pragma unroll
;         for (int di = 0; di < DV / 16; ++di) { bf16_t* yp = yrow + di * 16 + fq * 4; const u32x2 g = *(const u32x2*)yp;
;             f32x4 v = o[mi][di] * inv; v[0] *= bflo(g[0]); v[1] *= bfhi(g[0]); v[2] *= bflo(g[1]); v[3] *= bfhi(g[1]); if (!dry) store4(yp, v); }
;     }
.LBB0_664:
	s_or_b64 exec, exec, s[0:1]
	s_lshl_b64 s[0:1], s[8:9], 12
	s_add_u32 s0, s6, s0
	s_addc_u32 s1, s7, s1
	s_lshl_b32 s2, s55, 1
	s_waitcnt vmcnt(0)
	v_cmp_lt_i32_e32 vcc, v98, v102
	s_add_u32 s0, s0, s2
	s_addc_u32 s1, s1, 0
	v_cndmask_b32_e32 v0, v99, v98, vcc
	v_cmp_lt_i32_e32 vcc, v103, v102
	v_lshlrev_b32_e32 v14, 2, v0
	v_lshlrev_b32_e32 v160, 1, v134
	v_cndmask_b32_e32 v0, v99, v103, vcc
	v_lshlrev_b32_e32 v15, 2, v0
	v_lshl_add_u64 v[0:1], s[0:1], 0, v[160:161]
	s_mov_b64 s[0:1], 0x45b0400
	v_lshl_add_u64 v[2:3], v[0:1], 0, s[0:1]
	v_lshlrev_b64 v[4:5], 12, v[118:119]
	v_lshl_add_u64 v[4:5], v[2:3], 0, v[4:5]
	v_lshlrev_b64 v[6:7], 12, v[116:117]
	v_lshl_add_u64 v[6:7], v[2:3], 0, v[6:7]
	global_load_dwordx2 v[136:137], v[4:5], off
	global_load_dwordx2 v[138:139], v[4:5], off offset:32
	global_load_dwordx2 v[140:141], v[4:5], off offset:64
	global_load_dwordx2 v[142:143], v[4:5], off offset:96
	global_load_dwordx2 v[144:145], v[6:7], off
	global_load_dwordx2 v[146:147], v[6:7], off offset:32
	global_load_dwordx2 v[148:149], v[6:7], off offset:64
	global_load_dwordx2 v[150:151], v[6:7], off offset:96
	ds_bpermute_b32 v0, v14, v96
	ds_bpermute_b32 v8, v14, v97
	s_mov_b32 s0, s50
	s_waitcnt lgkmcnt(0)
	v_add_f32_e32 v0, v96, v0
	v_add_f32_e32 v8, v97, v8
	ds_bpermute_b32 v1, v15, v0
	ds_bpermute_b32 v9, v15, v8
	s_waitcnt lgkmcnt(0)
	v_add_f32_e32 v0, v0, v1
	v_add_f32_e32 v8, v8, v9
	v_rcp_f32_e32 v0, v0
	v_rcp_f32_e32 v8, v8
	s_waitcnt vmcnt(0)
	v_lshlrev_b32_e32 v152, 16, v136
	v_and_b32_e32 v153, 0xffff0000, v136
	v_lshlrev_b32_e32 v154, 16, v137
	v_and_b32_e32 v155, 0xffff0000, v137
	v_pk_mul_f32 v[88:89], v[88:89], v[0:1] op_sel_hi:[1,0]
	v_pk_mul_f32 v[90:91], v[90:91], v[0:1] op_sel_hi:[1,0]
	v_pk_mul_f32 v[88:89], v[88:89], v[152:153]
	v_pk_mul_f32 v[90:91], v[90:91], v[154:155]
	v_cvt_pk_bf16_f32 v88, v88, v89
	v_cvt_pk_bf16_f32 v89, v90, v91
	global_store_dwordx2 v[4:5], v[88:89], off
	v_lshlrev_b32_e32 v152, 16, v138
	v_and_b32_e32 v153, 0xffff0000, v138
	v_lshlrev_b32_e32 v154, 16, v139
	v_and_b32_e32 v155, 0xffff0000, v139
	v_pk_mul_f32 v[80:81], v[80:81], v[0:1] op_sel_hi:[1,0]
	v_pk_mul_f32 v[82:83], v[82:83], v[0:1] op_sel_hi:[1,0]
	v_pk_mul_f32 v[80:81], v[80:81], v[152:153]
	v_pk_mul_f32 v[82:83], v[82:83], v[154:155]
	v_cvt_pk_bf16_f32 v80, v80, v81
	v_cvt_pk_bf16_f32 v81, v82, v83
	global_store_dwordx2 v[4:5], v[80:81], off offset:32
	v_lshlrev_b32_e32 v152, 16, v140
	v_and_b32_e32 v153, 0xffff0000, v140
	v_lshlrev_b32_e32 v154, 16, v141
	v_and_b32_e32 v155, 0xffff0000, v141
	v_pk_mul_f32 v[60:61], v[60:61], v[0:1] op_sel_hi:[1,0]
	v_pk_mul_f32 v[62:63], v[62:63], v[0:1] op_sel_hi:[1,0]
	v_pk_mul_f32 v[60:61], v[60:61], v[152:153]
	v_pk_mul_f32 v[62:63], v[62:63], v[154:155]
	v_cvt_pk_bf16_f32 v60, v60, v61
	v_cvt_pk_bf16_f32 v61, v62, v63
	global_store_dwordx2 v[4:5], v[60:61], off offset:64
	v_lshlrev_b32_e32 v152, 16, v142
	v_and_b32_e32 v153, 0xffff0000, v142
	v_lshlrev_b32_e32 v154, 16, v143
	v_and_b32_e32 v155, 0xffff0000, v143
	v_pk_mul_f32 v[64:65], v[64:65], v[0:1] op_sel_hi:[1,0]
	v_pk_mul_f32 v[66:67], v[66:67], v[0:1] op_sel_hi:[1,0]
	v_pk_mul_f32 v[64:65], v[64:65], v[152:153]
	v_pk_mul_f32 v[66:67], v[66:67], v[154:155]
	v_cvt_pk_bf16_f32 v64, v64, v65
	v_cvt_pk_bf16_f32 v65, v66, v67
	global_store_dwordx2 v[4:5], v[64:65], off offset:96
	v_lshlrev_b32_e32 v152, 16, v144
	v_and_b32_e32 v153, 0xffff0000, v144
	v_lshlrev_b32_e32 v154, 16, v145
	v_and_b32_e32 v155, 0xffff0000, v145
	v_pk_mul_f32 v[48:49], v[48:49], v[8:9] op_sel_hi:[1,0]
	v_pk_mul_f32 v[50:51], v[50:51], v[8:9] op_sel_hi:[1,0]
	v_pk_mul_f32 v[48:49], v[48:49], v[152:153]
	v_pk_mul_f32 v[50:51], v[50:51], v[154:155]
	v_cvt_pk_bf16_f32 v48, v48, v49
	v_cvt_pk_bf16_f32 v49, v50, v51
	global_store_dwordx2 v[6:7], v[48:49], off
	v_lshlrev_b32_e32 v152, 16, v146
	v_and_b32_e32 v153, 0xffff0000, v146
	v_lshlrev_b32_e32 v154, 16, v147
	v_and_b32_e32 v155, 0xffff0000, v147
	v_pk_mul_f32 v[44:45], v[44:45], v[8:9] op_sel_hi:[1,0]
	v_pk_mul_f32 v[46:47], v[46:47], v[8:9] op_sel_hi:[1,0]
	v_pk_mul_f32 v[44:45], v[44:45], v[152:153]
	v_pk_mul_f32 v[46:47], v[46:47], v[154:155]
	v_cvt_pk_bf16_f32 v44, v44, v45
	v_cvt_pk_bf16_f32 v45, v46, v47
	global_store_dwordx2 v[6:7], v[44:45], off offset:32
	v_lshlrev_b32_e32 v152, 16, v148
	v_and_b32_e32 v153, 0xffff0000, v148
	v_lshlrev_b32_e32 v154, 16, v149
	v_and_b32_e32 v155, 0xffff0000, v149
	v_pk_mul_f32 v[36:37], v[36:37], v[8:9] op_sel_hi:[1,0]
	v_pk_mul_f32 v[38:39], v[38:39], v[8:9] op_sel_hi:[1,0]
	v_pk_mul_f32 v[36:37], v[36:37], v[152:153]
	v_pk_mul_f32 v[38:39], v[38:39], v[154:155]
	v_cvt_pk_bf16_f32 v36, v36, v37
	v_cvt_pk_bf16_f32 v37, v38, v39
	global_store_dwordx2 v[6:7], v[36:37], off offset:64
	v_lshlrev_b32_e32 v152, 16, v150
	v_and_b32_e32 v153, 0xffff0000, v150
	v_lshlrev_b32_e32 v154, 16, v151
	v_and_b32_e32 v155, 0xffff0000, v151
	v_pk_mul_f32 v[32:33], v[32:33], v[8:9] op_sel_hi:[1,0]
	v_pk_mul_f32 v[34:35], v[34:35], v[8:9] op_sel_hi:[1,0]
	v_pk_mul_f32 v[32:33], v[32:33], v[152:153]
	v_pk_mul_f32 v[34:35], v[34:35], v[154:155]
	v_cvt_pk_bf16_f32 v32, v32, v33
	v_cvt_pk_bf16_f32 v33, v34, v35
	global_store_dwordx2 v[6:7], v[32:33], off offset:96
	s_add_i32 s18, s0, s18
	s_cmpk_lt_i32 s18, 0x800
	s_cbranch_scc0 .LBB0_734
